# even-tile row-sum adds moved into the PV MFMA shadow before the barrier
# speedup vs baseline: 1.0473x; 1.0046x over previous
; __device__ __forceinline__ void attn_tile(const u16* sb, const bf16x8 (&qa)[6], f32x16& o0, f32x16& o1, f32x16& lacc,
;                                           float& m, bool& mz, int r, int h, bool first) {
;     ...
;   float pa = 0.f, pb = 0.f, pc = 0.f, pd = 0.f;
; #pragma unroll
;   for (int i = 0; i < 16; ++i) {
;     s0[i] = __builtin_amdgcn_exp2f(s0[i]); s1[i] = __builtin_amdgcn_exp2f(s1[i]);
;     if ((i & 3) == 0) pa += s0[i] + s1[i];
;     else if ((i & 3) == 1) pb += s0[i] + s1[i];
;     else if ((i & 3) == 2) pc += s0[i] + s1[i];
;     else pd += s0[i] + s1[i];
;   }
;   lacc[0] += (pa + pb) + (pc + pd);
;   const u16* vp = sb + 64 * KLD + r * VLD + 8 * h;
;   __builtin_amdgcn_s_setprio(1);
; #pragma unroll
;   for (int kb = 0; kb < 2; ++kb) {
; #pragma unroll
;     for (int s = 0; s < 2; ++s) {
;       const bf16x8 pf = pack_p(kb == 0 ? s0 : s1, 8 * s);
;       const int koff = kb * 32 + 16 * s;
;       const bf16x8 v0 = *(const bf16x8*)(vp + koff);
;       const bf16x8 v1 = *(const bf16x8*)(vp + 32 * VLD + koff);
;       o0 = mfma32(v0, pf, o0);
;       o1 = mfma32(v1, pf, o1);
;     }
;   }
;   __builtin_amdgcn_s_setprio(0);
; __device__ void item_attn(PP p, int qb, int b, int hh, u16* lds) {
;     ...
;     as_store(A, lds + ATT_STAGE, kl0, kl1, kl2, vl);
;     __syncthreads();
;     if (kt + 3 < ntiles) as_load(A, kg, vg, kt + 3);
;     if (kt + 1 < my_ntiles) attn_tile(lds + ATT_STAGE, qa, oa0, oa1, lacc, ma, mz, r, h, false);
.LBB0_464:
	v_exp_f32_e32 v147, v53
	v_exp_f32_e32 v149, v37
	v_exp_f32_e32 v145, v57
	v_exp_f32_e32 v53, v41
	v_exp_f32_e32 v143, v61
	v_exp_f32_e32 v45, v45
	v_exp_f32_e32 v37, v65
	v_exp_f32_e32 v41, v49
	v_exp_f32_e32 v146, v34
	v_exp_f32_e32 v152, v35
	v_exp_f32_e32 v153, v36
	v_exp_f32_e32 v144, v38
	v_exp_f32_e32 v150, v39
	v_exp_f32_e32 v151, v40
	v_exp_f32_e32 v142, v42
	v_exp_f32_e32 v38, v43
	v_exp_f32_e32 v39, v44
	v_exp_f32_e32 v36, v46
	v_exp_f32_e32 v34, v47
	v_exp_f32_e32 v35, v48
	v_exp_f32_e32 v148, v50
	v_exp_f32_e32 v50, v51
	v_exp_f32_e32 v51, v52
	v_exp_f32_e32 v52, v54
	v_exp_f32_e32 v48, v55
	v_exp_f32_e32 v49, v56
	v_exp_f32_e32 v44, v58
	v_exp_f32_e32 v46, v59
	v_exp_f32_e32 v47, v60
	v_exp_f32_e32 v40, v62
	v_exp_f32_e32 v42, v63
	v_exp_f32_e32 v43, v64
	s_setprio 1
	v_cvt_pk_bf16_f32 v58, v148, v50
	v_cvt_pk_bf16_f32 v59, v51, v147
	v_cvt_pk_bf16_f32 v60, v52, v48
	v_cvt_pk_bf16_f32 v61, v49, v145
	v_cvt_pk_bf16_f32 v246, v44, v46
	v_cvt_pk_bf16_f32 v247, v47, v143
	v_cvt_pk_bf16_f32 v248, v40, v42
	v_cvt_pk_bf16_f32 v249, v43, v37
	s_waitcnt lgkmcnt(0)
	v_mfma_f32_32x32x16_bf16 v[18:33], v[214:217], v[58:61], v[18:33]
	v_mfma_f32_32x32x16_bf16 v[2:17], v[218:221], v[58:61], v[2:17]
	v_cvt_pk_bf16_f32 v58, v146, v152
	v_cvt_pk_bf16_f32 v59, v153, v149
	v_cvt_pk_bf16_f32 v60, v144, v150
	v_cvt_pk_bf16_f32 v61, v151, v53
	v_mfma_f32_32x32x16_bf16 v[18:33], v[222:225], v[246:249], v[18:33]
	v_mfma_f32_32x32x16_bf16 v[2:17], v[226:229], v[246:249], v[2:17]
	v_cvt_pk_bf16_f32 v246, v142, v38
	v_cvt_pk_bf16_f32 v247, v39, v45
	v_cvt_pk_bf16_f32 v248, v36, v34
	v_cvt_pk_bf16_f32 v249, v35, v41
	v_mfma_f32_32x32x16_bf16 v[18:33], v[230:233], v[58:61], v[18:33]
	v_mfma_f32_32x32x16_bf16 v[2:17], v[234:237], v[58:61], v[2:17]
	v_mfma_f32_32x32x16_bf16 v[18:33], v[238:241], v[246:249], v[18:33]
	v_mfma_f32_32x32x16_bf16 v[2:17], v[242:245], v[246:249], v[2:17]
	s_setprio 0
	v_pk_add_f32 v[50:51], v[50:51], v[152:153]
	v_pk_add_f32 v[48:49], v[48:49], v[150:151]
	v_pk_add_f32 v[38:39], v[46:47], v[38:39]
	v_pk_add_f32 v[48:49], v[48:49], v[50:51]
	v_pk_add_f32 v[34:35], v[42:43], v[34:35]
	v_pk_add_f32 v[38:39], v[38:39], v[48:49]
	v_pk_add_f32 v[42:43], v[52:53], v[144:145]
	v_pk_add_f32 v[34:35], v[34:35], v[38:39]
	v_pk_add_f32 v[38:39], v[148:149], v[146:147]
	v_pk_add_f32 v[36:37], v[40:41], v[36:37]
	v_pk_add_f32 v[38:39], v[42:43], v[38:39]
	v_pk_add_f32 v[42:43], v[44:45], v[142:143]
	s_nop 0
	v_pk_add_f32 v[38:39], v[42:43], v[38:39]
	s_nop 0
	v_pk_add_f32 v[36:37], v[36:37], v[38:39]
	s_nop 0
	v_pk_add_f32 v[34:35], v[34:35], v[36:37]
	s_nop 0
	v_add_f32_e32 v34, v34, v35
	v_add_f32_e32 v136, v136, v34
	s_waitcnt vmcnt(0)
	s_cmp_ge_i32 s45, s44
	s_waitcnt lgkmcnt(0)
	s_barrier
	s_cbranch_scc1 .LBB0_466
.LBB0_466:
	v_cmp_lt_i32_e32 vcc, s45, v165
	s_and_saveexec_b64 s[40:41], vcc
	s_cbranch_execz .LBB0_475
	ds_read_b128 v[214:217], v90 offset:22528
	ds_read_b128 v[218:221], v90 offset:28672
	ds_read_b128 v[222:225], v91 offset:22528
	ds_read_b128 v[226:229], v91 offset:28672
	ds_read_b128 v[230:233], v92 offset:22528
	ds_read_b128 v[234:237], v92 offset:28672
	ds_read_b128 v[238:241], v93 offset:22528
	ds_read_b128 v[242:245], v93 offset:28672
	ds_read_b128 v[246:249], v94 offset:22528
	ds_read_b128 v[250:253], v94 offset:28672
	ds_read_b128 v[142:145], v95 offset:22528
	ds_read_b128 v[146:149], v95 offset:28672
	s_setprio 1
	s_cmp_lg_u64 s[48:49], 0
	s_cbranch_scc1 .Lmz_o
	v_xor_b32_e32 v34, 0x80000000, v162
	v_mov_b32_e32 v35, v34
	v_mov_b32_e32 v36, v34
	v_mov_b32_e32 v37, v34
	v_mov_b32_e32 v38, v34
	v_mov_b32_e32 v39, v34
	v_mov_b32_e32 v40, v34
	v_mov_b32_e32 v41, v34
	v_mov_b32_e32 v42, v34
	v_mov_b32_e32 v43, v34
	v_mov_b32_e32 v44, v34
	v_mov_b32_e32 v45, v34
	v_mov_b32_e32 v46, v34
	v_mov_b32_e32 v47, v34
	v_mov_b32_e32 v48, v34
	v_mov_b32_e32 v49, v34
	s_waitcnt lgkmcnt(8)
	s_nop 0
	v_mfma_f32_32x32x16_bf16 v[50:65], v[214:217], v[66:69], v[34:49]
	v_mfma_f32_32x32x16_bf16 v[34:49], v[218:221], v[66:69], v[34:49]
	v_mfma_f32_32x32x16_bf16 v[50:65], v[222:225], v[70:73], v[50:65]
	v_mfma_f32_32x32x16_bf16 v[34:49], v[226:229], v[70:73], v[34:49]
	s_waitcnt lgkmcnt(4)
	v_mfma_f32_32x32x16_bf16 v[50:65], v[230:233], v[74:77], v[50:65]
	v_mfma_f32_32x32x16_bf16 v[34:49], v[234:237], v[74:77], v[34:49]
	v_mfma_f32_32x32x16_bf16 v[50:65], v[238:241], v[78:81], v[50:65]
	v_mfma_f32_32x32x16_bf16 v[34:49], v[242:245], v[78:81], v[34:49]
	s_waitcnt lgkmcnt(0)
	v_mfma_f32_32x32x16_bf16 v[50:65], v[246:249], v[82:85], v[50:65]
	v_mfma_f32_32x32x16_bf16 v[34:49], v[250:253], v[82:85], v[34:49]
	v_mfma_f32_32x32x16_bf16 v[50:65], v[142:145], v[86:89], v[50:65]
	v_mfma_f32_32x32x16_bf16 v[34:49], v[146:149], v[86:89], v[34:49]
	s_branch .Lqkd_o
